# removed 120 redundant s_nop 0 pads after empty inline-asm blocks in attention PV gaps
# speedup vs baseline: 1.0009x; 1.0009x over previous
.LBB0_213:
	s_add_i32 s13, s93, 0xffff8000
	v_add_f32_e32 v228, v228, v0
	ds_read_b64_tr_b16 v[66:67], v226 offset:0
	ds_read_b64_tr_b16 v[68:69], v226 offset:512
	ds_read_b64_tr_b16 v[70:71], v226 offset:4096
	ds_read_b64_tr_b16 v[72:73], v226 offset:4608
	ds_read_b64_tr_b16 v[74:75], v226 offset:8192
	ds_read_b64_tr_b16 v[76:77], v226 offset:8704
	ds_read_b64_tr_b16 v[78:79], v226 offset:12288
	ds_read_b64_tr_b16 v[80:81], v226 offset:12800
	s_waitcnt lgkmcnt(6)
	s_nop 0
	s_add_i32 s12, s93, 0xffff8400
	v_mfma_f32_32x32x16_bf16 v[50:65], v[174:177], v[66:69], v[50:65]
	v_max3_f32 v0, v146, s92, v147
	v_exp_f32_e32 v146, v146
	v_exp_f32_e32 v147, v147
	s_add_i32 s29, s93, 0x2000
	ds_read_b64_tr_b16 v[66:67], v226 offset:1024
	ds_read_b64_tr_b16 v[68:69], v226 offset:1536
	s_waitcnt lgkmcnt(6)
	v_max3_f32 v0, v0, v148, v149
	v_mfma_f32_32x32x16_bf16 v[34:49], v[174:177], v[70:73], v[34:49]
	v_exp_f32_e32 v148, v148
	v_exp_f32_e32 v149, v149
	ds_read_b64_tr_b16 v[70:71], v226 offset:5120
	ds_read_b64_tr_b16 v[72:73], v226 offset:5632
	s_mov_b32 m0, s97
	s_waitcnt lgkmcnt(6)
	v_max3_f32 v0, v0, v150, v151
	buffer_load_dwordx4 v224, s[20:23], s93 offen lds
	v_mfma_f32_32x32x16_bf16 v[18:33], v[174:177], v[74:77], v[18:33]
	v_exp_f32_e32 v150, v150
	v_exp_f32_e32 v151, v151
	ds_read_b64_tr_b16 v[74:75], v226 offset:9216
	ds_read_b64_tr_b16 v[76:77], v226 offset:9728
	s_waitcnt lgkmcnt(6)
	v_max3_f32 v0, v0, v152, v153
	v_mfma_f32_32x32x16_bf16 v[2:17], v[174:177], v[78:81], v[2:17]
	v_exp_f32_e32 v152, v152
	v_exp_f32_e32 v153, v153
	ds_read_b64_tr_b16 v[78:79], v226 offset:13312
	ds_read_b64_tr_b16 v[80:81], v226 offset:13824
	s_waitcnt lgkmcnt(6)
	v_max3_f32 v0, v0, v154, v155
	v_mfma_f32_32x32x16_bf16 v[50:65], v[170:173], v[66:69], v[50:65]
	v_exp_f32_e32 v154, v154
	v_exp_f32_e32 v155, v155
	ds_read_b64_tr_b16 v[66:67], v226 offset:2048
	ds_read_b64_tr_b16 v[68:69], v226 offset:2560
	s_mov_b32 m0, s51
	s_waitcnt lgkmcnt(6)
	v_max3_f32 v0, v0, v156, v157
	buffer_load_dwordx4 v224, s[20:23], s29 offen lds
	v_mfma_f32_32x32x16_bf16 v[34:49], v[170:173], v[70:73], v[34:49]
	v_exp_f32_e32 v156, v156
	v_exp_f32_e32 v157, v157
	ds_read_b64_tr_b16 v[70:71], v226 offset:6144
	ds_read_b64_tr_b16 v[72:73], v226 offset:6656
	s_waitcnt lgkmcnt(6)
	v_max3_f32 v0, v0, v158, v159
	v_mfma_f32_32x32x16_bf16 v[18:33], v[170:173], v[74:77], v[18:33]
	v_exp_f32_e32 v158, v158
	v_exp_f32_e32 v159, v159
	ds_read_b64_tr_b16 v[74:75], v226 offset:10240
	ds_read_b64_tr_b16 v[76:77], v226 offset:10752
	s_waitcnt lgkmcnt(6)
	v_max3_f32 v0, v0, v160, v161
	v_mfma_f32_32x32x16_bf16 v[2:17], v[170:173], v[78:81], v[2:17]
	v_exp_f32_e32 v160, v160
	v_exp_f32_e32 v161, v161
	ds_read_b64_tr_b16 v[78:79], v226 offset:14336
	ds_read_b64_tr_b16 v[80:81], v226 offset:14848
	s_mov_b32 m0, s31
	s_waitcnt lgkmcnt(6)
	v_max3_f32 v0, v0, v130, v131
	buffer_load_dwordx4 v223, s[20:23], s13 offen lds
	v_mfma_f32_32x32x16_bf16 v[50:65], v[166:169], v[66:69], v[50:65]
	v_exp_f32_e32 v130, v130
	v_exp_f32_e32 v131, v131
	ds_read_b64_tr_b16 v[66:67], v226 offset:3072
	ds_read_b64_tr_b16 v[68:69], v226 offset:3584
	s_waitcnt lgkmcnt(6)
	v_max3_f32 v0, v0, v132, v133
	v_mfma_f32_32x32x16_bf16 v[34:49], v[166:169], v[70:73], v[34:49]
	v_exp_f32_e32 v132, v132
	v_exp_f32_e32 v133, v133
	ds_read_b64_tr_b16 v[70:71], v226 offset:7168
	ds_read_b64_tr_b16 v[72:73], v226 offset:7680
	s_waitcnt lgkmcnt(6)
	v_max3_f32 v0, v0, v134, v135
	v_mfma_f32_32x32x16_bf16 v[18:33], v[166:169], v[74:77], v[18:33]
	v_exp_f32_e32 v134, v134
	v_exp_f32_e32 v135, v135
	ds_read_b64_tr_b16 v[74:75], v226 offset:11264
	ds_read_b64_tr_b16 v[76:77], v226 offset:11776
	s_mov_b32 m0, s91
	s_waitcnt lgkmcnt(6)
	v_max3_f32 v0, v0, v136, v137
	buffer_load_dwordx4 v223, s[20:23], s12 offen lds
	v_mfma_f32_32x32x16_bf16 v[2:17], v[166:169], v[78:81], v[2:17]
	v_exp_f32_e32 v136, v136
	v_exp_f32_e32 v137, v137
	ds_read_b64_tr_b16 v[78:79], v226 offset:15360
	ds_read_b64_tr_b16 v[80:81], v226 offset:15872
	s_waitcnt lgkmcnt(6)
	v_max3_f32 v0, v0, v138, v139
	v_mfma_f32_32x32x16_bf16 v[50:65], v[162:165], v[66:69], v[50:65]
	v_exp_f32_e32 v138, v138
	v_exp_f32_e32 v139, v139
	s_waitcnt lgkmcnt(4)
	v_max3_f32 v0, v0, v140, v141
	v_mfma_f32_32x32x16_bf16 v[34:49], v[162:165], v[70:73], v[34:49]
	v_exp_f32_e32 v140, v140
	v_exp_f32_e32 v141, v141
	s_waitcnt lgkmcnt(2)
	v_max3_f32 v0, v0, v142, v143
	v_mfma_f32_32x32x16_bf16 v[18:33], v[162:165], v[74:77], v[18:33]
	v_exp_f32_e32 v142, v142
	v_exp_f32_e32 v143, v143
	s_waitcnt lgkmcnt(0)
	v_max3_f32 v0, v0, v144, v145
	v_mfma_f32_32x32x16_bf16 v[2:17], v[162:165], v[78:81], v[2:17]
	v_exp_f32_e32 v144, v144
	v_exp_f32_e32 v145, v145
	v_mov_b32_e32 v66, v0
	s_nop 1
	v_permlane32_swap_b32_e32 v0, v66
	v_max_f32_e32 v66, v66, v66
	v_max_f32_e32 v0, v0, v0
	v_max_f32_e32 v0, v0, v66
	v_cmp_lt_f32_e32 vcc, s33, v0
	s_cmp_eq_u64 vcc, 0
	s_cselect_b64 s[12:13], -1, 0
	s_cbranch_vccz .LBB0_217
	v_max_f32_e32 v0, v0, v0
	v_max_f32_e32 v66, 0, v0
	v_exp_f32_e64 v0, -v66
	s_and_saveexec_b64 s[80:81], s[4:5]
	ds_write_b32 v213, v0
	s_or_b64 exec, exec, s[80:81]
	s_waitcnt lgkmcnt(0)
	v_add_f32_e32 v222, v222, v66
	ds_read_b128 v[66:69], v212
	ds_read_b128 v[70:73], v212 offset:32
	ds_read_b128 v[74:77], v212 offset:64
	ds_read_b128 v[78:81], v212 offset:96
	v_mul_f32_e32 v228, v228, v0
	s_waitcnt lgkmcnt(3)
	v_pk_mul_f32 v[52:53], v[52:53], v[68:69]
	s_waitcnt lgkmcnt(2)
	v_pk_mul_f32 v[56:57], v[56:57], v[72:73]
	s_waitcnt lgkmcnt(1)
	v_pk_mul_f32 v[60:61], v[60:61], v[76:77]
	s_waitcnt lgkmcnt(0)
	v_pk_mul_f32 v[64:65], v[64:65], v[80:81]
	v_pk_mul_f32 v[62:63], v[62:63], v[78:79]
	v_pk_mul_f32 v[58:59], v[58:59], v[74:75]
	v_pk_mul_f32 v[54:55], v[54:55], v[70:71]
	v_pk_mul_f32 v[50:51], v[50:51], v[66:67]
	v_pk_mul_f32 v[48:49], v[48:49], v[80:81]
	v_pk_mul_f32 v[44:45], v[44:45], v[76:77]
	v_pk_mul_f32 v[40:41], v[40:41], v[72:73]
	v_pk_mul_f32 v[36:37], v[36:37], v[68:69]
	v_pk_mul_f32 v[46:47], v[46:47], v[78:79]
	v_pk_mul_f32 v[42:43], v[42:43], v[74:75]
	v_pk_mul_f32 v[38:39], v[38:39], v[70:71]
	v_pk_mul_f32 v[34:35], v[34:35], v[66:67]
	v_pk_mul_f32 v[32:33], v[32:33], v[80:81]
	v_pk_mul_f32 v[28:29], v[28:29], v[76:77]
	v_pk_mul_f32 v[24:25], v[24:25], v[72:73]
	v_pk_mul_f32 v[20:21], v[20:21], v[68:69]
	v_pk_mul_f32 v[30:31], v[30:31], v[78:79]
	v_pk_mul_f32 v[26:27], v[26:27], v[74:75]
	v_pk_mul_f32 v[22:23], v[22:23], v[70:71]
	v_pk_mul_f32 v[18:19], v[18:19], v[66:67]
	v_pk_mul_f32 v[16:17], v[16:17], v[80:81]
	v_pk_mul_f32 v[12:13], v[12:13], v[76:77]
	v_pk_mul_f32 v[8:9], v[8:9], v[72:73]
	v_pk_mul_f32 v[4:5], v[4:5], v[68:69]
	v_pk_mul_f32 v[14:15], v[14:15], v[78:79]
	v_pk_mul_f32 v[10:11], v[10:11], v[74:75]
	v_pk_mul_f32 v[6:7], v[6:7], v[70:71]
	v_pk_mul_f32 v[2:3], v[2:3], v[66:67]
	v_pk_mul_f32 v[160:161], v[160:161], v[0:1] op_sel_hi:[1,0]
	v_pk_mul_f32 v[158:159], v[158:159], v[0:1] op_sel_hi:[1,0]
	v_pk_mul_f32 v[156:157], v[156:157], v[0:1] op_sel_hi:[1,0]
	v_pk_mul_f32 v[154:155], v[154:155], v[0:1] op_sel_hi:[1,0]
	v_pk_mul_f32 v[152:153], v[152:153], v[0:1] op_sel_hi:[1,0]
	v_pk_mul_f32 v[150:151], v[150:151], v[0:1] op_sel_hi:[1,0]
	v_pk_mul_f32 v[148:149], v[148:149], v[0:1] op_sel_hi:[1,0]
	v_pk_mul_f32 v[146:147], v[146:147], v[0:1] op_sel_hi:[1,0]
	v_pk_mul_f32 v[144:145], v[144:145], v[0:1] op_sel_hi:[1,0]
	v_pk_mul_f32 v[142:143], v[142:143], v[0:1] op_sel_hi:[1,0]
	v_pk_mul_f32 v[140:141], v[140:141], v[0:1] op_sel_hi:[1,0]
	v_pk_mul_f32 v[138:139], v[138:139], v[0:1] op_sel_hi:[1,0]
	v_pk_mul_f32 v[136:137], v[136:137], v[0:1] op_sel_hi:[1,0]
	v_pk_mul_f32 v[134:135], v[134:135], v[0:1] op_sel_hi:[1,0]
	v_pk_mul_f32 v[132:133], v[132:133], v[0:1] op_sel_hi:[1,0]
	v_pk_mul_f32 v[130:131], v[130:131], v[0:1] op_sel_hi:[1,0]

.LBB0_222:
	v_add_f32_e32 v228, v228, v0
	ds_read_b64_tr_b16 v[130:131], v225 offset:0
	ds_read_b64_tr_b16 v[132:133], v225 offset:512
	ds_read_b64_tr_b16 v[134:135], v225 offset:4096
	ds_read_b64_tr_b16 v[136:137], v225 offset:4608
	ds_read_b64_tr_b16 v[138:139], v225 offset:8192
	ds_read_b64_tr_b16 v[140:141], v225 offset:8704
	ds_read_b64_tr_b16 v[142:143], v225 offset:12288
	ds_read_b64_tr_b16 v[144:145], v225 offset:12800
	s_waitcnt lgkmcnt(6)
	v_max3_f32 v0, v114, s92, v115
	v_mfma_f32_32x32x16_bf16 v[50:65], v[174:177], v[130:133], v[50:65]
	v_exp_f32_e32 v114, v114
	v_exp_f32_e32 v115, v115
	ds_read_b64_tr_b16 v[130:131], v225 offset:1024
	ds_read_b64_tr_b16 v[132:133], v225 offset:1536
	s_waitcnt lgkmcnt(6)
	v_max3_f32 v0, v0, v116, v117
	v_mfma_f32_32x32x16_bf16 v[34:49], v[174:177], v[134:137], v[34:49]
	v_exp_f32_e32 v116, v116
	v_exp_f32_e32 v117, v117
	ds_read_b64_tr_b16 v[134:135], v225 offset:5120
	ds_read_b64_tr_b16 v[136:137], v225 offset:5632
	s_waitcnt lgkmcnt(6)
	v_max3_f32 v0, v0, v118, v119
	v_mfma_f32_32x32x16_bf16 v[18:33], v[174:177], v[138:141], v[18:33]
	v_exp_f32_e32 v118, v118
	v_exp_f32_e32 v119, v119
	ds_read_b64_tr_b16 v[138:139], v225 offset:9216
	ds_read_b64_tr_b16 v[140:141], v225 offset:9728
	s_waitcnt lgkmcnt(6)
	v_max3_f32 v0, v0, v120, v121
	v_mfma_f32_32x32x16_bf16 v[2:17], v[174:177], v[142:145], v[2:17]
	v_exp_f32_e32 v120, v120
	v_exp_f32_e32 v121, v121
	ds_read_b64_tr_b16 v[142:143], v225 offset:13312
	ds_read_b64_tr_b16 v[144:145], v225 offset:13824
	s_waitcnt lgkmcnt(6)
	v_max3_f32 v0, v0, v122, v123
	v_mfma_f32_32x32x16_bf16 v[50:65], v[170:173], v[130:133], v[50:65]
	v_exp_f32_e32 v122, v122
	v_exp_f32_e32 v123, v123
	ds_read_b64_tr_b16 v[130:131], v225 offset:2048
	ds_read_b64_tr_b16 v[132:133], v225 offset:2560
	s_waitcnt lgkmcnt(6)
	v_max3_f32 v0, v0, v124, v125
	v_mfma_f32_32x32x16_bf16 v[34:49], v[170:173], v[134:137], v[34:49]
	v_exp_f32_e32 v124, v124
	v_exp_f32_e32 v125, v125
	ds_read_b64_tr_b16 v[134:135], v225 offset:6144
	ds_read_b64_tr_b16 v[136:137], v225 offset:6656
	s_waitcnt lgkmcnt(6)
	v_max3_f32 v0, v0, v126, v127
	v_mfma_f32_32x32x16_bf16 v[18:33], v[170:173], v[138:141], v[18:33]
	v_exp_f32_e32 v126, v126
	v_exp_f32_e32 v127, v127
	ds_read_b64_tr_b16 v[138:139], v225 offset:10240
	ds_read_b64_tr_b16 v[140:141], v225 offset:10752
	s_waitcnt lgkmcnt(6)
	v_max3_f32 v0, v0, v128, v129
	v_mfma_f32_32x32x16_bf16 v[2:17], v[170:173], v[142:145], v[2:17]
	v_exp_f32_e32 v128, v128
	v_exp_f32_e32 v129, v129
	ds_read_b64_tr_b16 v[142:143], v225 offset:14336
	ds_read_b64_tr_b16 v[144:145], v225 offset:14848
	s_waitcnt lgkmcnt(6)
	v_max3_f32 v0, v0, v98, v99
	v_mfma_f32_32x32x16_bf16 v[50:65], v[166:169], v[130:133], v[50:65]
	v_exp_f32_e32 v98, v98
	v_exp_f32_e32 v99, v99
	ds_read_b64_tr_b16 v[130:131], v225 offset:3072
	ds_read_b64_tr_b16 v[132:133], v225 offset:3584
	s_waitcnt lgkmcnt(6)
	v_max3_f32 v0, v0, v100, v101
	v_mfma_f32_32x32x16_bf16 v[34:49], v[166:169], v[134:137], v[34:49]
	v_exp_f32_e32 v100, v100
	v_exp_f32_e32 v101, v101
	ds_read_b64_tr_b16 v[134:135], v225 offset:7168
	ds_read_b64_tr_b16 v[136:137], v225 offset:7680
	s_waitcnt lgkmcnt(6)
	v_max3_f32 v0, v0, v102, v103
	v_mfma_f32_32x32x16_bf16 v[18:33], v[166:169], v[138:141], v[18:33]
	v_exp_f32_e32 v102, v102
	v_exp_f32_e32 v103, v103
	ds_read_b64_tr_b16 v[138:139], v225 offset:11264
	ds_read_b64_tr_b16 v[140:141], v225 offset:11776
	s_waitcnt lgkmcnt(6)
	v_max3_f32 v0, v0, v104, v105
	v_mfma_f32_32x32x16_bf16 v[2:17], v[166:169], v[142:145], v[2:17]
	v_exp_f32_e32 v104, v104
	v_exp_f32_e32 v105, v105
	ds_read_b64_tr_b16 v[142:143], v225 offset:15360
	ds_read_b64_tr_b16 v[144:145], v225 offset:15872
	s_waitcnt lgkmcnt(6)
	v_max3_f32 v0, v0, v106, v107
	v_mfma_f32_32x32x16_bf16 v[50:65], v[162:165], v[130:133], v[50:65]
	v_exp_f32_e32 v106, v106
	v_exp_f32_e32 v107, v107
	s_waitcnt lgkmcnt(4)
	v_max3_f32 v0, v0, v108, v109
	v_mfma_f32_32x32x16_bf16 v[34:49], v[162:165], v[134:137], v[34:49]
	v_exp_f32_e32 v108, v108
	v_exp_f32_e32 v109, v109
	s_waitcnt lgkmcnt(2)
	v_max3_f32 v0, v0, v110, v111
	v_mfma_f32_32x32x16_bf16 v[18:33], v[162:165], v[138:141], v[18:33]
	v_exp_f32_e32 v110, v110
	v_exp_f32_e32 v111, v111
	s_waitcnt lgkmcnt(0)
	v_max3_f32 v0, v0, v112, v113
	v_mfma_f32_32x32x16_bf16 v[2:17], v[162:165], v[142:145], v[2:17]
	v_exp_f32_e32 v112, v112
	v_exp_f32_e32 v113, v113
	v_mov_b32_e32 v130, v0
	s_nop 1
	v_permlane32_swap_b32_e32 v0, v130
	v_max_f32_e32 v130, v130, v130
	v_max_f32_e32 v0, v0, v0
	v_max_f32_e32 v0, v0, v130
	v_cmp_lt_f32_e32 vcc, s33, v0
	s_cmp_eq_u64 vcc, 0
	s_cselect_b64 s[12:13], -1, 0
	s_cbranch_vccnz .LBB0_240
	s_andn2_b64 vcc, exec, s[12:13]
	s_mov_b64 s[12:13], -1
	s_cbranch_vccz .LBB0_243

.LBB0_228:
	s_add_i32 s65, s93, 0x10000
	v_add_f32_e32 v228, v228, v0
	ds_read_b64_tr_b16 v[98:99], v215 offset:0
	ds_read_b64_tr_b16 v[100:101], v215 offset:512
	ds_read_b64_tr_b16 v[102:103], v215 offset:4096
	ds_read_b64_tr_b16 v[104:105], v215 offset:4608
	ds_read_b64_tr_b16 v[106:107], v215 offset:8192
	ds_read_b64_tr_b16 v[108:109], v215 offset:8704
	ds_read_b64_tr_b16 v[110:111], v215 offset:12288
	ds_read_b64_tr_b16 v[112:113], v215 offset:12800
	s_waitcnt lgkmcnt(6)
	s_nop 0
	s_add_i32 s12, s93, 0x8400
	v_mfma_f32_32x32x16_bf16 v[50:65], v[174:177], v[98:101], v[50:65]
	s_add_i32 s13, s93, 0x12000
	v_max3_f32 v0, v146, s92, v147
	v_exp_f32_e32 v146, v146
	v_exp_f32_e32 v147, v147
	ds_read_b64_tr_b16 v[98:99], v215 offset:1024
	ds_read_b64_tr_b16 v[100:101], v215 offset:1536
	s_waitcnt lgkmcnt(6)
	v_max3_f32 v0, v0, v148, v149
	v_mfma_f32_32x32x16_bf16 v[34:49], v[174:177], v[102:105], v[34:49]
	v_exp_f32_e32 v148, v148
	v_exp_f32_e32 v149, v149
	ds_read_b64_tr_b16 v[102:103], v215 offset:5120
	ds_read_b64_tr_b16 v[104:105], v215 offset:5632
	s_mov_b32 m0, s54
	s_waitcnt lgkmcnt(6)
	v_max3_f32 v0, v0, v150, v151
	buffer_load_dwordx4 v224, s[20:23], s65 offen lds
	v_mfma_f32_32x32x16_bf16 v[18:33], v[174:177], v[106:109], v[18:33]
	v_exp_f32_e32 v150, v150
	v_exp_f32_e32 v151, v151
	ds_read_b64_tr_b16 v[106:107], v215 offset:9216
	ds_read_b64_tr_b16 v[108:109], v215 offset:9728
	s_waitcnt lgkmcnt(6)
	v_max3_f32 v0, v0, v152, v153
	v_mfma_f32_32x32x16_bf16 v[2:17], v[174:177], v[110:113], v[2:17]
	v_exp_f32_e32 v152, v152
	v_exp_f32_e32 v153, v153
	ds_read_b64_tr_b16 v[110:111], v215 offset:13312
	ds_read_b64_tr_b16 v[112:113], v215 offset:13824
	s_waitcnt lgkmcnt(6)
	v_max3_f32 v0, v0, v154, v155
	v_mfma_f32_32x32x16_bf16 v[50:65], v[170:173], v[98:101], v[50:65]
	v_exp_f32_e32 v154, v154
	v_exp_f32_e32 v155, v155
	ds_read_b64_tr_b16 v[98:99], v215 offset:2048
	ds_read_b64_tr_b16 v[100:101], v215 offset:2560
	s_mov_b32 m0, s55
	s_waitcnt lgkmcnt(6)
	v_max3_f32 v0, v0, v156, v157
	buffer_load_dwordx4 v224, s[20:23], s13 offen lds
	v_mfma_f32_32x32x16_bf16 v[34:49], v[170:173], v[102:105], v[34:49]
	v_exp_f32_e32 v156, v156
	v_exp_f32_e32 v157, v157
	ds_read_b64_tr_b16 v[102:103], v215 offset:6144
	ds_read_b64_tr_b16 v[104:105], v215 offset:6656
	s_waitcnt lgkmcnt(6)
	v_max3_f32 v0, v0, v158, v159
	v_mfma_f32_32x32x16_bf16 v[18:33], v[170:173], v[106:109], v[18:33]
	v_exp_f32_e32 v158, v158
	v_exp_f32_e32 v159, v159
	ds_read_b64_tr_b16 v[106:107], v215 offset:10240
	ds_read_b64_tr_b16 v[108:109], v215 offset:10752
	s_waitcnt lgkmcnt(6)
	v_max3_f32 v0, v0, v160, v161
	v_mfma_f32_32x32x16_bf16 v[2:17], v[170:173], v[110:113], v[2:17]
	v_exp_f32_e32 v160, v160
	v_exp_f32_e32 v161, v161
	ds_read_b64_tr_b16 v[110:111], v215 offset:14336
	ds_read_b64_tr_b16 v[112:113], v215 offset:14848
	s_mov_b32 m0, s57
	s_waitcnt lgkmcnt(6)
	v_max3_f32 v0, v0, v130, v131
	buffer_load_dwordx4 v223, s[20:23], s64 offen lds
	v_mfma_f32_32x32x16_bf16 v[50:65], v[166:169], v[98:101], v[50:65]
	v_exp_f32_e32 v130, v130
	v_exp_f32_e32 v131, v131
	ds_read_b64_tr_b16 v[98:99], v215 offset:3072
	ds_read_b64_tr_b16 v[100:101], v215 offset:3584
	s_waitcnt lgkmcnt(6)
	v_max3_f32 v0, v0, v132, v133
	v_mfma_f32_32x32x16_bf16 v[34:49], v[166:169], v[102:105], v[34:49]
	v_exp_f32_e32 v132, v132
	v_exp_f32_e32 v133, v133
	ds_read_b64_tr_b16 v[102:103], v215 offset:7168
	ds_read_b64_tr_b16 v[104:105], v215 offset:7680
	s_waitcnt lgkmcnt(6)
	v_max3_f32 v0, v0, v134, v135
	v_mfma_f32_32x32x16_bf16 v[18:33], v[166:169], v[106:109], v[18:33]
	v_exp_f32_e32 v134, v134
	v_exp_f32_e32 v135, v135
	ds_read_b64_tr_b16 v[106:107], v215 offset:11264
	ds_read_b64_tr_b16 v[108:109], v215 offset:11776
	s_mov_b32 m0, s99
	s_waitcnt lgkmcnt(6)
	v_max3_f32 v0, v0, v136, v137
	buffer_load_dwordx4 v223, s[20:23], s12 offen lds
	v_mfma_f32_32x32x16_bf16 v[2:17], v[166:169], v[110:113], v[2:17]
	v_exp_f32_e32 v136, v136
	v_exp_f32_e32 v137, v137
	ds_read_b64_tr_b16 v[110:111], v215 offset:15360
	ds_read_b64_tr_b16 v[112:113], v215 offset:15872
	s_waitcnt lgkmcnt(6)
	v_max3_f32 v0, v0, v138, v139
	v_mfma_f32_32x32x16_bf16 v[50:65], v[162:165], v[98:101], v[50:65]
	v_exp_f32_e32 v138, v138
	v_exp_f32_e32 v139, v139
	s_waitcnt lgkmcnt(4)
	v_max3_f32 v0, v0, v140, v141
	v_mfma_f32_32x32x16_bf16 v[34:49], v[162:165], v[102:105], v[34:49]
	v_exp_f32_e32 v140, v140
	v_exp_f32_e32 v141, v141
	s_waitcnt lgkmcnt(2)
	v_max3_f32 v0, v0, v142, v143
	v_mfma_f32_32x32x16_bf16 v[18:33], v[162:165], v[106:109], v[18:33]
	v_exp_f32_e32 v142, v142
	v_exp_f32_e32 v143, v143
	s_waitcnt lgkmcnt(0)
	v_max3_f32 v0, v0, v144, v145
	v_mfma_f32_32x32x16_bf16 v[2:17], v[162:165], v[110:113], v[2:17]
	v_exp_f32_e32 v144, v144
	v_exp_f32_e32 v145, v145
	v_mov_b32_e32 v98, v0
	s_nop 1
	v_permlane32_swap_b32_e32 v0, v98
	v_max_f32_e32 v98, v98, v98
	v_max_f32_e32 v0, v0, v0
	v_max_f32_e32 v0, v0, v98
	v_cmp_lt_f32_e32 vcc, s33, v0
	s_cmp_eq_u64 vcc, 0
	s_cselect_b64 s[12:13], -1, 0
	s_cbranch_vccnz .LBB0_244
	s_andn2_b64 vcc, exec, s[12:13]
	s_mov_b64 s[12:13], -1
	s_cbranch_vccz .LBB0_247

.LBB0_234:
	v_add_f32_e32 v228, v228, v0
	ds_read_b64_tr_b16 v[130:131], v214 offset:0
	ds_read_b64_tr_b16 v[132:133], v214 offset:512
	ds_read_b64_tr_b16 v[134:135], v214 offset:4096
	ds_read_b64_tr_b16 v[136:137], v214 offset:4608
	ds_read_b64_tr_b16 v[138:139], v214 offset:8192
	ds_read_b64_tr_b16 v[140:141], v214 offset:8704
	ds_read_b64_tr_b16 v[142:143], v214 offset:12288
	ds_read_b64_tr_b16 v[144:145], v214 offset:12800
	s_waitcnt lgkmcnt(6)
	v_max3_f32 v0, v114, s92, v115
	v_mfma_f32_32x32x16_bf16 v[50:65], v[174:177], v[130:133], v[50:65]
	v_exp_f32_e32 v114, v114
	v_exp_f32_e32 v115, v115
	ds_read_b64_tr_b16 v[130:131], v214 offset:1024
	ds_read_b64_tr_b16 v[132:133], v214 offset:1536
	s_waitcnt lgkmcnt(6)
	v_max3_f32 v0, v0, v116, v117
	v_mfma_f32_32x32x16_bf16 v[34:49], v[174:177], v[134:137], v[34:49]
	v_exp_f32_e32 v116, v116
	v_exp_f32_e32 v117, v117
	ds_read_b64_tr_b16 v[134:135], v214 offset:5120
	ds_read_b64_tr_b16 v[136:137], v214 offset:5632
	s_waitcnt lgkmcnt(6)
	v_max3_f32 v0, v0, v118, v119
	v_mfma_f32_32x32x16_bf16 v[18:33], v[174:177], v[138:141], v[18:33]
	v_exp_f32_e32 v118, v118
	v_exp_f32_e32 v119, v119
	ds_read_b64_tr_b16 v[138:139], v214 offset:9216
	ds_read_b64_tr_b16 v[140:141], v214 offset:9728
	s_waitcnt lgkmcnt(6)
	v_max3_f32 v0, v0, v120, v121
	v_mfma_f32_32x32x16_bf16 v[2:17], v[174:177], v[142:145], v[2:17]
	v_exp_f32_e32 v120, v120
	v_exp_f32_e32 v121, v121
	ds_read_b64_tr_b16 v[142:143], v214 offset:13312
	ds_read_b64_tr_b16 v[144:145], v214 offset:13824
	s_waitcnt lgkmcnt(6)
	v_max3_f32 v0, v0, v122, v123
	v_mfma_f32_32x32x16_bf16 v[50:65], v[170:173], v[130:133], v[50:65]
	v_exp_f32_e32 v122, v122
	v_exp_f32_e32 v123, v123
	ds_read_b64_tr_b16 v[130:131], v214 offset:2048
	ds_read_b64_tr_b16 v[132:133], v214 offset:2560
	s_waitcnt lgkmcnt(6)
	v_max3_f32 v0, v0, v124, v125
	v_mfma_f32_32x32x16_bf16 v[34:49], v[170:173], v[134:137], v[34:49]
	v_exp_f32_e32 v124, v124
	v_exp_f32_e32 v125, v125
	ds_read_b64_tr_b16 v[134:135], v214 offset:6144
	ds_read_b64_tr_b16 v[136:137], v214 offset:6656
	s_waitcnt lgkmcnt(6)
	v_max3_f32 v0, v0, v126, v127
	v_mfma_f32_32x32x16_bf16 v[18:33], v[170:173], v[138:141], v[18:33]
	v_exp_f32_e32 v126, v126
	v_exp_f32_e32 v127, v127
	ds_read_b64_tr_b16 v[138:139], v214 offset:10240
	ds_read_b64_tr_b16 v[140:141], v214 offset:10752
	s_waitcnt lgkmcnt(6)
	v_max3_f32 v0, v0, v128, v129
	v_mfma_f32_32x32x16_bf16 v[2:17], v[170:173], v[142:145], v[2:17]
	v_exp_f32_e32 v128, v128
	v_exp_f32_e32 v129, v129
	ds_read_b64_tr_b16 v[142:143], v214 offset:14336
	ds_read_b64_tr_b16 v[144:145], v214 offset:14848
	s_waitcnt lgkmcnt(6)
	v_max3_f32 v0, v0, v98, v99
	v_mfma_f32_32x32x16_bf16 v[50:65], v[166:169], v[130:133], v[50:65]
	v_exp_f32_e32 v98, v98
	v_exp_f32_e32 v99, v99
	ds_read_b64_tr_b16 v[130:131], v214 offset:3072
	ds_read_b64_tr_b16 v[132:133], v214 offset:3584
	s_waitcnt lgkmcnt(6)
	v_max3_f32 v0, v0, v100, v101
	v_mfma_f32_32x32x16_bf16 v[34:49], v[166:169], v[134:137], v[34:49]
	v_exp_f32_e32 v100, v100
	v_exp_f32_e32 v101, v101
	ds_read_b64_tr_b16 v[134:135], v214 offset:7168
	ds_read_b64_tr_b16 v[136:137], v214 offset:7680
	s_waitcnt lgkmcnt(6)
	v_max3_f32 v0, v0, v102, v103
	v_mfma_f32_32x32x16_bf16 v[18:33], v[166:169], v[138:141], v[18:33]
	v_exp_f32_e32 v102, v102
	v_exp_f32_e32 v103, v103
	ds_read_b64_tr_b16 v[138:139], v214 offset:11264
	ds_read_b64_tr_b16 v[140:141], v214 offset:11776
	s_waitcnt lgkmcnt(6)
	v_max3_f32 v0, v0, v104, v105
	v_mfma_f32_32x32x16_bf16 v[2:17], v[166:169], v[142:145], v[2:17]
	v_exp_f32_e32 v104, v104
	v_exp_f32_e32 v105, v105
	ds_read_b64_tr_b16 v[142:143], v214 offset:15360
	ds_read_b64_tr_b16 v[144:145], v214 offset:15872
	s_waitcnt lgkmcnt(6)
	v_max3_f32 v0, v0, v106, v107
	v_mfma_f32_32x32x16_bf16 v[50:65], v[162:165], v[130:133], v[50:65]
	v_exp_f32_e32 v106, v106
	v_exp_f32_e32 v107, v107
	s_waitcnt lgkmcnt(4)
	v_max3_f32 v0, v0, v108, v109
	v_mfma_f32_32x32x16_bf16 v[34:49], v[162:165], v[134:137], v[34:49]
	v_exp_f32_e32 v108, v108
	v_exp_f32_e32 v109, v109
	s_waitcnt lgkmcnt(2)
	v_max3_f32 v0, v0, v110, v111
	v_mfma_f32_32x32x16_bf16 v[18:33], v[162:165], v[138:141], v[18:33]
	v_exp_f32_e32 v110, v110
	v_exp_f32_e32 v111, v111
	s_waitcnt lgkmcnt(0)
	v_max3_f32 v0, v0, v112, v113
	v_mfma_f32_32x32x16_bf16 v[2:17], v[162:165], v[142:145], v[2:17]
	v_exp_f32_e32 v112, v112
	v_exp_f32_e32 v113, v113
	v_mov_b32_e32 v130, v0
	s_nop 1
	v_permlane32_swap_b32_e32 v0, v130
	v_max_f32_e32 v130, v130, v130
	v_max_f32_e32 v0, v0, v0
	v_max_f32_e32 v0, v0, v130
	v_cmp_lt_f32_e32 vcc, s33, v0
	s_cmp_eq_u64 vcc, 0
	s_cselect_b64 s[12:13], -1, 0
	s_cbranch_vccnz .LBB0_248
	s_andn2_b64 vcc, exec, s[12:13]
	s_mov_b64 s[12:13], -1
	s_cbranch_vccz .LBB0_251

.LBB0_255:
	s_movk_i32 s87, 0x2000
	v_add_f32_e32 v147, v228, v0
	ds_read_b64_tr_b16 v[98:99], v226 offset:0
	ds_read_b64_tr_b16 v[100:101], v226 offset:512
	ds_read_b64_tr_b16 v[102:103], v226 offset:4096
	ds_read_b64_tr_b16 v[104:105], v226 offset:4608
	ds_read_b64_tr_b16 v[106:107], v226 offset:8192
	ds_read_b64_tr_b16 v[108:109], v226 offset:8704
	ds_read_b64_tr_b16 v[110:111], v226 offset:12288
	ds_read_b64_tr_b16 v[112:113], v226 offset:12800
	s_waitcnt lgkmcnt(6)
	v_max3_f32 v0, v130, s92, v131
	v_mfma_f32_32x32x16_bf16 v[50:65], v[174:177], v[98:101], v[50:65]
	v_exp_f32_e32 v130, v130
	v_exp_f32_e32 v131, v131
	ds_read_b64_tr_b16 v[98:99], v226 offset:1024
	ds_read_b64_tr_b16 v[100:101], v226 offset:1536
	s_waitcnt lgkmcnt(6)
	v_max3_f32 v0, v0, v132, v133
	v_mfma_f32_32x32x16_bf16 v[34:49], v[174:177], v[102:105], v[34:49]
	v_exp_f32_e32 v132, v132
	v_exp_f32_e32 v133, v133
	ds_read_b64_tr_b16 v[102:103], v226 offset:5120
	ds_read_b64_tr_b16 v[104:105], v226 offset:5632
	s_mov_b32 m0, s97
	s_waitcnt lgkmcnt(6)
	v_max3_f32 v0, v0, v134, v135
	buffer_load_dwordx4 v224, s[20:23], s58 offen lds
	v_mfma_f32_32x32x16_bf16 v[18:33], v[174:177], v[106:109], v[18:33]
	v_exp_f32_e32 v134, v134
	v_exp_f32_e32 v135, v135
	ds_read_b64_tr_b16 v[106:107], v226 offset:9216
	ds_read_b64_tr_b16 v[108:109], v226 offset:9728
	s_waitcnt lgkmcnt(6)
	v_max3_f32 v0, v0, v136, v137
	v_mfma_f32_32x32x16_bf16 v[2:17], v[174:177], v[110:113], v[2:17]
	v_exp_f32_e32 v136, v136
	v_exp_f32_e32 v137, v137
	ds_read_b64_tr_b16 v[110:111], v226 offset:13312
	ds_read_b64_tr_b16 v[112:113], v226 offset:13824
	s_waitcnt lgkmcnt(6)
	v_max3_f32 v0, v0, v138, v139
	v_mfma_f32_32x32x16_bf16 v[50:65], v[170:173], v[98:101], v[50:65]
	v_exp_f32_e32 v138, v138
	v_exp_f32_e32 v139, v139
	ds_read_b64_tr_b16 v[98:99], v226 offset:2048
	ds_read_b64_tr_b16 v[100:101], v226 offset:2560
	s_mov_b32 m0, s51
	v_readlane_b32 s10, v229, 25
	s_waitcnt lgkmcnt(6)
	v_max3_f32 v0, v0, v140, v141
	v_mfma_f32_32x32x16_bf16 v[34:49], v[170:173], v[102:105], v[34:49]
	v_exp_f32_e32 v140, v140
	s_nop 1
	buffer_load_dwordx4 v224, s[20:23], s10 offen lds
	v_exp_f32_e32 v141, v141
	ds_read_b64_tr_b16 v[102:103], v226 offset:6144
	ds_read_b64_tr_b16 v[104:105], v226 offset:6656
	s_waitcnt lgkmcnt(6)
	v_max3_f32 v0, v0, v142, v143
	v_mfma_f32_32x32x16_bf16 v[18:33], v[170:173], v[106:109], v[18:33]
	v_exp_f32_e32 v142, v142
	v_exp_f32_e32 v143, v143
	ds_read_b64_tr_b16 v[106:107], v226 offset:10240
	ds_read_b64_tr_b16 v[108:109], v226 offset:10752
	s_waitcnt lgkmcnt(6)
	v_max3_f32 v0, v0, v144, v145
	v_mfma_f32_32x32x16_bf16 v[2:17], v[170:173], v[110:113], v[2:17]
	v_exp_f32_e32 v144, v144
	v_exp_f32_e32 v145, v145
	ds_read_b64_tr_b16 v[110:111], v226 offset:14336
	ds_read_b64_tr_b16 v[112:113], v226 offset:14848
	s_mov_b32 m0, s31
	v_readlane_b32 s10, v229, 21
	s_waitcnt lgkmcnt(6)
	v_max3_f32 v0, v0, v82, v83
	v_mfma_f32_32x32x16_bf16 v[50:65], v[166:169], v[98:101], v[50:65]
	v_exp_f32_e32 v82, v82
	s_nop 1
	buffer_load_dwordx4 v223, s[20:23], s10 offen lds
	v_exp_f32_e32 v83, v83
	ds_read_b64_tr_b16 v[98:99], v226 offset:3072
	ds_read_b64_tr_b16 v[100:101], v226 offset:3584
	s_waitcnt lgkmcnt(6)
	v_max3_f32 v0, v0, v84, v85
	v_mfma_f32_32x32x16_bf16 v[34:49], v[166:169], v[102:105], v[34:49]
	v_exp_f32_e32 v84, v84
	v_exp_f32_e32 v85, v85
	ds_read_b64_tr_b16 v[102:103], v226 offset:7168
	ds_read_b64_tr_b16 v[104:105], v226 offset:7680
	s_waitcnt lgkmcnt(6)
	v_max3_f32 v0, v0, v86, v87
	v_mfma_f32_32x32x16_bf16 v[18:33], v[166:169], v[106:109], v[18:33]
	v_exp_f32_e32 v86, v86
	v_exp_f32_e32 v87, v87
	ds_read_b64_tr_b16 v[106:107], v226 offset:11264
	ds_read_b64_tr_b16 v[108:109], v226 offset:11776
	s_mov_b32 m0, s91
	v_readlane_b32 s10, v229, 24
	s_waitcnt lgkmcnt(6)
	v_max3_f32 v0, v0, v88, v89
	v_mfma_f32_32x32x16_bf16 v[2:17], v[166:169], v[110:113], v[2:17]
	v_exp_f32_e32 v88, v88
	s_nop 1
	buffer_load_dwordx4 v223, s[20:23], s10 offen lds
	v_exp_f32_e32 v89, v89
	ds_read_b64_tr_b16 v[110:111], v226 offset:15360
	ds_read_b64_tr_b16 v[112:113], v226 offset:15872
	s_waitcnt lgkmcnt(6)
	v_max3_f32 v0, v0, v90, v91
	v_mfma_f32_32x32x16_bf16 v[50:65], v[162:165], v[98:101], v[50:65]
	v_exp_f32_e32 v90, v90
	v_exp_f32_e32 v91, v91
	s_waitcnt lgkmcnt(4)
	v_max3_f32 v0, v0, v92, v93
	v_mfma_f32_32x32x16_bf16 v[34:49], v[162:165], v[102:105], v[34:49]
	v_exp_f32_e32 v92, v92
	v_exp_f32_e32 v93, v93
	s_waitcnt lgkmcnt(2)
	v_max3_f32 v0, v0, v94, v95
	v_mfma_f32_32x32x16_bf16 v[18:33], v[162:165], v[106:109], v[18:33]
	v_exp_f32_e32 v94, v94
	v_exp_f32_e32 v95, v95
	s_waitcnt lgkmcnt(0)
	v_max3_f32 v0, v0, v96, v97
	v_mfma_f32_32x32x16_bf16 v[2:17], v[162:165], v[110:113], v[2:17]
	v_exp_f32_e32 v96, v96
	v_exp_f32_e32 v97, v97
	v_mov_b32_e32 v98, v0
	s_nop 1
	v_permlane32_swap_b32_e32 v0, v98
	v_max_f32_e32 v98, v98, v98
	v_max_f32_e32 v0, v0, v0
	v_max_f32_e32 v0, v0, v98
	v_cmp_lt_f32_e32 vcc, s33, v0
	s_cmp_lg_u64 vcc, 0
	s_cselect_b64 s[12:13], -1, 0
	s_cbranch_vccz .LBB0_260
	v_max_f32_e32 v0, v0, v0
	v_max_f32_e32 v98, 0, v0
	v_exp_f32_e64 v0, -v98
	s_and_saveexec_b64 s[80:81], s[4:5]
	s_movk_i32 s31, 0x1000
	ds_write_b32 v213, v0
	s_or_b64 exec, exec, s[80:81]
	s_waitcnt lgkmcnt(0)
	v_add_f32_e32 v222, v222, v98
	ds_read_b128 v[98:101], v212
	ds_read_b128 v[102:105], v212 offset:32
	ds_read_b128 v[106:109], v212 offset:64
	ds_read_b128 v[110:113], v212 offset:96
	v_mul_f32_e32 v147, v147, v0
	s_waitcnt lgkmcnt(3)
	v_pk_mul_f32 v[52:53], v[52:53], v[100:101]
	s_waitcnt lgkmcnt(2)
	v_pk_mul_f32 v[56:57], v[56:57], v[104:105]
	s_waitcnt lgkmcnt(1)
	v_pk_mul_f32 v[60:61], v[60:61], v[108:109]
	s_waitcnt lgkmcnt(0)
	v_pk_mul_f32 v[64:65], v[64:65], v[112:113]
	v_pk_mul_f32 v[62:63], v[62:63], v[110:111]
	v_pk_mul_f32 v[58:59], v[58:59], v[106:107]
	v_pk_mul_f32 v[54:55], v[54:55], v[102:103]
	v_pk_mul_f32 v[50:51], v[50:51], v[98:99]
	v_pk_mul_f32 v[48:49], v[48:49], v[112:113]
	v_pk_mul_f32 v[44:45], v[44:45], v[108:109]
	v_pk_mul_f32 v[40:41], v[40:41], v[104:105]
	v_pk_mul_f32 v[36:37], v[36:37], v[100:101]
	v_pk_mul_f32 v[46:47], v[46:47], v[110:111]
	v_pk_mul_f32 v[42:43], v[42:43], v[106:107]
	v_pk_mul_f32 v[38:39], v[38:39], v[102:103]
	v_pk_mul_f32 v[34:35], v[34:35], v[98:99]
	v_pk_mul_f32 v[32:33], v[32:33], v[112:113]
	v_pk_mul_f32 v[28:29], v[28:29], v[108:109]
	v_pk_mul_f32 v[24:25], v[24:25], v[104:105]
	v_pk_mul_f32 v[20:21], v[20:21], v[100:101]
	v_pk_mul_f32 v[30:31], v[30:31], v[110:111]
	v_pk_mul_f32 v[26:27], v[26:27], v[106:107]
	v_pk_mul_f32 v[22:23], v[22:23], v[102:103]
	v_pk_mul_f32 v[18:19], v[18:19], v[98:99]
	v_pk_mul_f32 v[16:17], v[16:17], v[112:113]
	v_pk_mul_f32 v[12:13], v[12:13], v[108:109]
	v_pk_mul_f32 v[8:9], v[8:9], v[104:105]
	v_pk_mul_f32 v[4:5], v[4:5], v[100:101]
	v_pk_mul_f32 v[14:15], v[14:15], v[110:111]
	v_pk_mul_f32 v[10:11], v[10:11], v[106:107]
	v_pk_mul_f32 v[6:7], v[6:7], v[102:103]
	v_pk_mul_f32 v[2:3], v[2:3], v[98:99]
	v_pk_mul_f32 v[144:145], v[144:145], v[0:1] op_sel_hi:[1,0]
	v_pk_mul_f32 v[142:143], v[142:143], v[0:1] op_sel_hi:[1,0]
	v_pk_mul_f32 v[140:141], v[140:141], v[0:1] op_sel_hi:[1,0]
	v_pk_mul_f32 v[138:139], v[138:139], v[0:1] op_sel_hi:[1,0]
	v_pk_mul_f32 v[136:137], v[136:137], v[0:1] op_sel_hi:[1,0]
	v_pk_mul_f32 v[134:135], v[134:135], v[0:1] op_sel_hi:[1,0]
	v_pk_mul_f32 v[132:133], v[132:133], v[0:1] op_sel_hi:[1,0]
	v_pk_mul_f32 v[130:131], v[130:131], v[0:1] op_sel_hi:[1,0]
	v_pk_mul_f32 v[96:97], v[96:97], v[0:1] op_sel_hi:[1,0]
	v_pk_mul_f32 v[94:95], v[94:95], v[0:1] op_sel_hi:[1,0]
	v_pk_mul_f32 v[92:93], v[92:93], v[0:1] op_sel_hi:[1,0]
	v_pk_mul_f32 v[90:91], v[90:91], v[0:1] op_sel_hi:[1,0]
	v_pk_mul_f32 v[88:89], v[88:89], v[0:1] op_sel_hi:[1,0]
	v_pk_mul_f32 v[86:87], v[86:87], v[0:1] op_sel_hi:[1,0]
	v_pk_mul_f32 v[84:85], v[84:85], v[0:1] op_sel_hi:[1,0]
	v_pk_mul_f32 v[82:83], v[82:83], v[0:1] op_sel_hi:[1,0]
	s_andn2_b64 vcc, exec, s[12:13]
	s_cbranch_vccnz .LBB0_261

.LBB0_268:
	v_add_f32_e32 v130, v147, v0
	ds_read_b64_tr_b16 v[82:83], v225 offset:0
	ds_read_b64_tr_b16 v[84:85], v225 offset:512
	ds_read_b64_tr_b16 v[86:87], v225 offset:4096
	ds_read_b64_tr_b16 v[88:89], v225 offset:4608
	ds_read_b64_tr_b16 v[90:91], v225 offset:8192
	ds_read_b64_tr_b16 v[92:93], v225 offset:8704
	ds_read_b64_tr_b16 v[94:95], v225 offset:12288
	ds_read_b64_tr_b16 v[96:97], v225 offset:12800
	s_waitcnt lgkmcnt(6)
	v_max3_f32 v0, v114, s92, v115
	v_mfma_f32_32x32x16_bf16 v[50:65], v[174:177], v[82:85], v[50:65]
	v_exp_f32_e32 v114, v114
	v_exp_f32_e32 v115, v115
	ds_read_b64_tr_b16 v[82:83], v225 offset:1024
	ds_read_b64_tr_b16 v[84:85], v225 offset:1536
	s_waitcnt lgkmcnt(6)
	v_max3_f32 v0, v0, v116, v117
	v_mfma_f32_32x32x16_bf16 v[34:49], v[174:177], v[86:89], v[34:49]
	v_exp_f32_e32 v116, v116
	v_exp_f32_e32 v117, v117
	ds_read_b64_tr_b16 v[86:87], v225 offset:5120
	ds_read_b64_tr_b16 v[88:89], v225 offset:5632
	s_waitcnt lgkmcnt(6)
	v_max3_f32 v0, v0, v118, v119
	v_mfma_f32_32x32x16_bf16 v[18:33], v[174:177], v[90:93], v[18:33]
	v_exp_f32_e32 v118, v118
	v_exp_f32_e32 v119, v119
	ds_read_b64_tr_b16 v[90:91], v225 offset:9216
	ds_read_b64_tr_b16 v[92:93], v225 offset:9728
	s_waitcnt lgkmcnt(6)
	v_max3_f32 v0, v0, v120, v121
	v_mfma_f32_32x32x16_bf16 v[2:17], v[174:177], v[94:97], v[2:17]
	v_exp_f32_e32 v120, v120
	v_exp_f32_e32 v121, v121
	ds_read_b64_tr_b16 v[94:95], v225 offset:13312
	ds_read_b64_tr_b16 v[96:97], v225 offset:13824
	s_waitcnt lgkmcnt(6)
	v_max3_f32 v0, v0, v122, v123
	v_mfma_f32_32x32x16_bf16 v[50:65], v[170:173], v[82:85], v[50:65]
	v_exp_f32_e32 v122, v122
	v_exp_f32_e32 v123, v123
	ds_read_b64_tr_b16 v[82:83], v225 offset:2048
	ds_read_b64_tr_b16 v[84:85], v225 offset:2560
	s_waitcnt lgkmcnt(6)
	v_max3_f32 v0, v0, v124, v125
	v_mfma_f32_32x32x16_bf16 v[34:49], v[170:173], v[86:89], v[34:49]
	v_exp_f32_e32 v124, v124
	v_exp_f32_e32 v125, v125
	ds_read_b64_tr_b16 v[86:87], v225 offset:6144
	ds_read_b64_tr_b16 v[88:89], v225 offset:6656
	s_waitcnt lgkmcnt(6)
	v_max3_f32 v0, v0, v126, v127
	v_mfma_f32_32x32x16_bf16 v[18:33], v[170:173], v[90:93], v[18:33]
	v_exp_f32_e32 v126, v126
	v_exp_f32_e32 v127, v127
	ds_read_b64_tr_b16 v[90:91], v225 offset:10240
	ds_read_b64_tr_b16 v[92:93], v225 offset:10752
	s_waitcnt lgkmcnt(6)
	v_max3_f32 v0, v0, v128, v129
	v_mfma_f32_32x32x16_bf16 v[2:17], v[170:173], v[94:97], v[2:17]
	v_exp_f32_e32 v128, v128
	v_exp_f32_e32 v129, v129
	ds_read_b64_tr_b16 v[94:95], v225 offset:14336
	ds_read_b64_tr_b16 v[96:97], v225 offset:14848
	s_waitcnt lgkmcnt(6)
	v_max3_f32 v0, v0, v98, v99
	v_mfma_f32_32x32x16_bf16 v[50:65], v[166:169], v[82:85], v[50:65]
	v_exp_f32_e32 v98, v98
	v_exp_f32_e32 v99, v99
	ds_read_b64_tr_b16 v[82:83], v225 offset:3072
	ds_read_b64_tr_b16 v[84:85], v225 offset:3584
	s_waitcnt lgkmcnt(6)
	v_max3_f32 v0, v0, v100, v101
	v_mfma_f32_32x32x16_bf16 v[34:49], v[166:169], v[86:89], v[34:49]
	v_exp_f32_e32 v100, v100
	v_exp_f32_e32 v101, v101
	ds_read_b64_tr_b16 v[86:87], v225 offset:7168
	ds_read_b64_tr_b16 v[88:89], v225 offset:7680
	s_waitcnt lgkmcnt(6)
	v_max3_f32 v0, v0, v102, v103
	v_mfma_f32_32x32x16_bf16 v[18:33], v[166:169], v[90:93], v[18:33]
	v_exp_f32_e32 v102, v102
	v_exp_f32_e32 v103, v103
	ds_read_b64_tr_b16 v[90:91], v225 offset:11264
	ds_read_b64_tr_b16 v[92:93], v225 offset:11776
	s_waitcnt lgkmcnt(6)
	v_max3_f32 v0, v0, v104, v105
	v_mfma_f32_32x32x16_bf16 v[2:17], v[166:169], v[94:97], v[2:17]
	v_exp_f32_e32 v104, v104
	v_exp_f32_e32 v105, v105
	ds_read_b64_tr_b16 v[94:95], v225 offset:15360
	ds_read_b64_tr_b16 v[96:97], v225 offset:15872
	s_waitcnt lgkmcnt(6)
	v_max3_f32 v0, v0, v106, v107
	v_mfma_f32_32x32x16_bf16 v[50:65], v[162:165], v[82:85], v[50:65]
	v_exp_f32_e32 v106, v106
	v_exp_f32_e32 v107, v107
	s_waitcnt lgkmcnt(4)
	v_max3_f32 v0, v0, v108, v109
	v_mfma_f32_32x32x16_bf16 v[34:49], v[162:165], v[86:89], v[34:49]
	v_exp_f32_e32 v108, v108
	v_exp_f32_e32 v109, v109
	s_waitcnt lgkmcnt(2)
	v_max3_f32 v0, v0, v110, v111
	v_mfma_f32_32x32x16_bf16 v[18:33], v[162:165], v[90:93], v[18:33]
	v_exp_f32_e32 v110, v110
	v_exp_f32_e32 v111, v111
	s_waitcnt lgkmcnt(0)
	v_max3_f32 v0, v0, v112, v113
	v_mfma_f32_32x32x16_bf16 v[2:17], v[162:165], v[94:97], v[2:17]
	v_exp_f32_e32 v112, v112
	v_exp_f32_e32 v113, v113
	v_mov_b32_e32 v82, v0
	s_nop 1
	v_permlane32_swap_b32_e32 v0, v82
	v_max_f32_e32 v82, v82, v82
	v_max_f32_e32 v0, v0, v0
	v_max_f32_e32 v0, v0, v82
	v_cmp_lt_f32_e32 vcc, s33, v0
	s_cmp_lg_u64 vcc, 0
	s_cselect_b64 s[12:13], -1, 0
	s_cbranch_vccz .LBB0_272
	v_max_f32_e32 v0, v0, v0
	v_max_f32_e32 v82, 0, v0
	v_exp_f32_e64 v0, -v82
	s_and_saveexec_b64 s[20:21], s[4:5]
	ds_write_b32 v213, v0
	s_or_b64 exec, exec, s[20:21]
	s_waitcnt lgkmcnt(0)
	v_add_f32_e32 v222, v222, v82
	ds_read_b128 v[82:85], v212
	ds_read_b128 v[86:89], v212 offset:32
	ds_read_b128 v[90:93], v212 offset:64
	ds_read_b128 v[94:97], v212 offset:96
	v_mul_f32_e32 v130, v130, v0
	s_waitcnt lgkmcnt(3)
	v_pk_mul_f32 v[52:53], v[52:53], v[84:85]
	s_waitcnt lgkmcnt(2)
	v_pk_mul_f32 v[56:57], v[56:57], v[88:89]
	s_waitcnt lgkmcnt(1)
	v_pk_mul_f32 v[60:61], v[60:61], v[92:93]
	s_waitcnt lgkmcnt(0)
	v_pk_mul_f32 v[64:65], v[64:65], v[96:97]
	v_pk_mul_f32 v[62:63], v[62:63], v[94:95]
	v_pk_mul_f32 v[58:59], v[58:59], v[90:91]
	v_pk_mul_f32 v[54:55], v[54:55], v[86:87]
	v_pk_mul_f32 v[50:51], v[50:51], v[82:83]
	v_pk_mul_f32 v[48:49], v[48:49], v[96:97]
	v_pk_mul_f32 v[44:45], v[44:45], v[92:93]
	v_pk_mul_f32 v[40:41], v[40:41], v[88:89]
	v_pk_mul_f32 v[36:37], v[36:37], v[84:85]
	v_pk_mul_f32 v[46:47], v[46:47], v[94:95]
	v_pk_mul_f32 v[42:43], v[42:43], v[90:91]
	v_pk_mul_f32 v[38:39], v[38:39], v[86:87]
	v_pk_mul_f32 v[34:35], v[34:35], v[82:83]
	v_pk_mul_f32 v[32:33], v[32:33], v[96:97]
	v_pk_mul_f32 v[28:29], v[28:29], v[92:93]
	v_pk_mul_f32 v[24:25], v[24:25], v[88:89]
	v_pk_mul_f32 v[20:21], v[20:21], v[84:85]
	v_pk_mul_f32 v[30:31], v[30:31], v[94:95]
	v_pk_mul_f32 v[26:27], v[26:27], v[90:91]
	v_pk_mul_f32 v[22:23], v[22:23], v[86:87]
	v_pk_mul_f32 v[18:19], v[18:19], v[82:83]
	v_pk_mul_f32 v[16:17], v[16:17], v[96:97]
	v_pk_mul_f32 v[12:13], v[12:13], v[92:93]
	v_pk_mul_f32 v[8:9], v[8:9], v[88:89]
	v_pk_mul_f32 v[4:5], v[4:5], v[84:85]
	v_pk_mul_f32 v[14:15], v[14:15], v[94:95]
	v_pk_mul_f32 v[10:11], v[10:11], v[90:91]
	v_pk_mul_f32 v[6:7], v[6:7], v[86:87]
	v_pk_mul_f32 v[2:3], v[2:3], v[82:83]
	v_pk_mul_f32 v[128:129], v[128:129], v[0:1] op_sel_hi:[1,0]
	v_pk_mul_f32 v[126:127], v[126:127], v[0:1] op_sel_hi:[1,0]
	v_pk_mul_f32 v[124:125], v[124:125], v[0:1] op_sel_hi:[1,0]
	v_pk_mul_f32 v[122:123], v[122:123], v[0:1] op_sel_hi:[1,0]
	v_pk_mul_f32 v[120:121], v[120:121], v[0:1] op_sel_hi:[1,0]
	v_pk_mul_f32 v[118:119], v[118:119], v[0:1] op_sel_hi:[1,0]
	v_pk_mul_f32 v[116:117], v[116:117], v[0:1] op_sel_hi:[1,0]
	v_pk_mul_f32 v[114:115], v[114:115], v[0:1] op_sel_hi:[1,0]
	v_pk_mul_f32 v[112:113], v[112:113], v[0:1] op_sel_hi:[1,0]
	v_pk_mul_f32 v[110:111], v[110:111], v[0:1] op_sel_hi:[1,0]
	v_pk_mul_f32 v[108:109], v[108:109], v[0:1] op_sel_hi:[1,0]
	v_pk_mul_f32 v[106:107], v[106:107], v[0:1] op_sel_hi:[1,0]
	v_pk_mul_f32 v[104:105], v[104:105], v[0:1] op_sel_hi:[1,0]
	v_pk_mul_f32 v[102:103], v[102:103], v[0:1] op_sel_hi:[1,0]
	v_pk_mul_f32 v[100:101], v[100:101], v[0:1] op_sel_hi:[1,0]
	v_pk_mul_f32 v[98:99], v[98:99], v[0:1] op_sel_hi:[1,0]

.LBB0_279:
	v_add_f32_e32 v98, v130, v0
	ds_read_b64_tr_b16 v[100:101], v215 offset:0
	ds_read_b64_tr_b16 v[102:103], v215 offset:512
	ds_read_b64_tr_b16 v[104:105], v215 offset:4096
	ds_read_b64_tr_b16 v[106:107], v215 offset:4608
	ds_read_b64_tr_b16 v[108:109], v215 offset:8192
	ds_read_b64_tr_b16 v[110:111], v215 offset:8704
	ds_read_b64_tr_b16 v[112:113], v215 offset:12288
	ds_read_b64_tr_b16 v[114:115], v215 offset:12800
	s_waitcnt lgkmcnt(6)
	v_max3_f32 v0, v82, s92, v83
	v_mfma_f32_32x32x16_bf16 v[50:65], v[174:177], v[100:103], v[50:65]
	v_exp_f32_e32 v82, v82
	v_exp_f32_e32 v83, v83
	ds_read_b64_tr_b16 v[100:101], v215 offset:1024
	ds_read_b64_tr_b16 v[102:103], v215 offset:1536
	s_waitcnt lgkmcnt(6)
	v_max3_f32 v0, v0, v84, v85
	v_mfma_f32_32x32x16_bf16 v[34:49], v[174:177], v[104:107], v[34:49]
	v_exp_f32_e32 v84, v84
	v_exp_f32_e32 v85, v85
	ds_read_b64_tr_b16 v[104:105], v215 offset:5120
	ds_read_b64_tr_b16 v[106:107], v215 offset:5632
	s_waitcnt lgkmcnt(6)
	v_max3_f32 v0, v0, v86, v87
	v_mfma_f32_32x32x16_bf16 v[18:33], v[174:177], v[108:111], v[18:33]
	v_exp_f32_e32 v86, v86
	v_exp_f32_e32 v87, v87
	ds_read_b64_tr_b16 v[108:109], v215 offset:9216
	ds_read_b64_tr_b16 v[110:111], v215 offset:9728
	s_waitcnt lgkmcnt(6)
	v_max3_f32 v0, v0, v88, v89
	v_mfma_f32_32x32x16_bf16 v[2:17], v[174:177], v[112:115], v[2:17]
	v_exp_f32_e32 v88, v88
	v_exp_f32_e32 v89, v89
	ds_read_b64_tr_b16 v[112:113], v215 offset:13312
	ds_read_b64_tr_b16 v[114:115], v215 offset:13824
	s_waitcnt lgkmcnt(6)
	v_max3_f32 v0, v0, v90, v91
	v_mfma_f32_32x32x16_bf16 v[50:65], v[170:173], v[100:103], v[50:65]
	v_exp_f32_e32 v90, v90
	v_exp_f32_e32 v91, v91
	ds_read_b64_tr_b16 v[100:101], v215 offset:2048
	ds_read_b64_tr_b16 v[102:103], v215 offset:2560
	s_waitcnt lgkmcnt(6)
	v_max3_f32 v0, v0, v92, v93
	v_mfma_f32_32x32x16_bf16 v[34:49], v[170:173], v[104:107], v[34:49]
	v_exp_f32_e32 v92, v92
	v_exp_f32_e32 v93, v93
	ds_read_b64_tr_b16 v[104:105], v215 offset:6144
	ds_read_b64_tr_b16 v[106:107], v215 offset:6656
	s_waitcnt lgkmcnt(6)
	v_max3_f32 v0, v0, v94, v95
	v_mfma_f32_32x32x16_bf16 v[18:33], v[170:173], v[108:111], v[18:33]
	v_exp_f32_e32 v94, v94
	v_exp_f32_e32 v95, v95
	ds_read_b64_tr_b16 v[108:109], v215 offset:10240
	ds_read_b64_tr_b16 v[110:111], v215 offset:10752
	s_waitcnt lgkmcnt(6)
	v_max3_f32 v0, v0, v96, v97
	v_mfma_f32_32x32x16_bf16 v[2:17], v[170:173], v[112:115], v[2:17]
	v_exp_f32_e32 v96, v96
	v_exp_f32_e32 v97, v97
	ds_read_b64_tr_b16 v[112:113], v215 offset:14336
	ds_read_b64_tr_b16 v[114:115], v215 offset:14848
	s_waitcnt lgkmcnt(6)
	v_max3_f32 v0, v0, v66, v67
	v_mfma_f32_32x32x16_bf16 v[50:65], v[166:169], v[100:103], v[50:65]
	v_exp_f32_e32 v66, v66
	v_exp_f32_e32 v67, v67
	ds_read_b64_tr_b16 v[100:101], v215 offset:3072
	ds_read_b64_tr_b16 v[102:103], v215 offset:3584
	s_waitcnt lgkmcnt(6)
	v_max3_f32 v0, v0, v68, v69
	v_mfma_f32_32x32x16_bf16 v[34:49], v[166:169], v[104:107], v[34:49]
	v_exp_f32_e32 v68, v68
	v_exp_f32_e32 v69, v69
	ds_read_b64_tr_b16 v[104:105], v215 offset:7168
	ds_read_b64_tr_b16 v[106:107], v215 offset:7680
	s_waitcnt lgkmcnt(6)
	v_max3_f32 v0, v0, v70, v71
	v_mfma_f32_32x32x16_bf16 v[18:33], v[166:169], v[108:111], v[18:33]
	v_exp_f32_e32 v70, v70
	v_exp_f32_e32 v71, v71
	ds_read_b64_tr_b16 v[108:109], v215 offset:11264
	ds_read_b64_tr_b16 v[110:111], v215 offset:11776
	s_waitcnt lgkmcnt(6)
	v_max3_f32 v0, v0, v72, v73
	v_mfma_f32_32x32x16_bf16 v[2:17], v[166:169], v[112:115], v[2:17]
	v_exp_f32_e32 v72, v72
	v_exp_f32_e32 v73, v73
	ds_read_b64_tr_b16 v[112:113], v215 offset:15360
	ds_read_b64_tr_b16 v[114:115], v215 offset:15872
	s_waitcnt lgkmcnt(6)
	v_max3_f32 v0, v0, v74, v75
	v_mfma_f32_32x32x16_bf16 v[50:65], v[162:165], v[100:103], v[50:65]
	v_exp_f32_e32 v74, v74
	v_exp_f32_e32 v75, v75
	s_waitcnt lgkmcnt(4)
	v_max3_f32 v0, v0, v76, v77
	v_mfma_f32_32x32x16_bf16 v[34:49], v[162:165], v[104:107], v[34:49]
	v_exp_f32_e32 v76, v76
	v_exp_f32_e32 v77, v77
	s_waitcnt lgkmcnt(2)
	v_max3_f32 v0, v0, v78, v79
	v_mfma_f32_32x32x16_bf16 v[18:33], v[162:165], v[108:111], v[18:33]
	v_exp_f32_e32 v78, v78
	v_exp_f32_e32 v79, v79
	s_waitcnt lgkmcnt(0)
	v_max3_f32 v0, v0, v80, v81
	v_mfma_f32_32x32x16_bf16 v[2:17], v[162:165], v[112:115], v[2:17]
	v_exp_f32_e32 v80, v80
	v_exp_f32_e32 v81, v81
	v_mov_b32_e32 v99, v0
	s_nop 1
	v_permlane32_swap_b32_e32 v0, v99
	v_max_f32_e32 v99, v99, v99
	v_max_f32_e32 v0, v0, v0
	v_max_f32_e32 v0, v0, v99
	v_cmp_lt_f32_e32 vcc, s33, v0
	s_cbranch_vccz .LBB0_283
	v_max_f32_e32 v0, v0, v0
	v_max_f32_e32 v0, 0, v0
	v_exp_f32_e64 v0, -v0
	s_and_saveexec_b64 s[6:7], s[4:5]
	ds_write_b32 v213, v0
	s_or_b64 exec, exec, s[6:7]
	s_waitcnt lgkmcnt(0)
	ds_read_b128 v[100:103], v212 offset:96
	ds_read_b128 v[104:107], v212 offset:64
	ds_read_b128 v[108:111], v212 offset:32
	ds_read_b128 v[112:115], v212
	v_mul_f32_e32 v98, v98, v0
	s_waitcnt lgkmcnt(3)
	v_pk_mul_f32 v[64:65], v[64:65], v[102:103]
	s_waitcnt lgkmcnt(2)
	v_pk_mul_f32 v[60:61], v[60:61], v[106:107]
	s_waitcnt lgkmcnt(1)
	v_pk_mul_f32 v[56:57], v[56:57], v[110:111]
	s_waitcnt lgkmcnt(0)
	v_pk_mul_f32 v[52:53], v[52:53], v[114:115]
	v_pk_mul_f32 v[62:63], v[62:63], v[100:101]
	v_pk_mul_f32 v[58:59], v[58:59], v[104:105]
	v_pk_mul_f32 v[54:55], v[54:55], v[108:109]
	v_pk_mul_f32 v[50:51], v[50:51], v[112:113]
	v_pk_mul_f32 v[48:49], v[48:49], v[102:103]
	v_pk_mul_f32 v[44:45], v[44:45], v[106:107]
	v_pk_mul_f32 v[40:41], v[40:41], v[110:111]
	v_pk_mul_f32 v[36:37], v[36:37], v[114:115]
	v_pk_mul_f32 v[46:47], v[46:47], v[100:101]
	v_pk_mul_f32 v[42:43], v[42:43], v[104:105]
	v_pk_mul_f32 v[38:39], v[38:39], v[108:109]
	v_pk_mul_f32 v[34:35], v[34:35], v[112:113]
	v_pk_mul_f32 v[32:33], v[32:33], v[102:103]
	v_pk_mul_f32 v[28:29], v[28:29], v[106:107]
	v_pk_mul_f32 v[24:25], v[24:25], v[110:111]
	v_pk_mul_f32 v[20:21], v[20:21], v[114:115]
	v_pk_mul_f32 v[30:31], v[30:31], v[100:101]
	v_pk_mul_f32 v[26:27], v[26:27], v[104:105]
	v_pk_mul_f32 v[22:23], v[22:23], v[108:109]
	v_pk_mul_f32 v[18:19], v[18:19], v[112:113]
	v_pk_mul_f32 v[16:17], v[16:17], v[102:103]
	v_pk_mul_f32 v[12:13], v[12:13], v[106:107]
	v_pk_mul_f32 v[8:9], v[8:9], v[110:111]
	v_pk_mul_f32 v[4:5], v[4:5], v[114:115]
	v_pk_mul_f32 v[14:15], v[14:15], v[100:101]
	v_pk_mul_f32 v[10:11], v[10:11], v[104:105]
	v_pk_mul_f32 v[6:7], v[6:7], v[108:109]
	v_pk_mul_f32 v[2:3], v[2:3], v[112:113]
	v_pk_mul_f32 v[96:97], v[96:97], v[0:1] op_sel_hi:[1,0]
	v_pk_mul_f32 v[94:95], v[94:95], v[0:1] op_sel_hi:[1,0]
	v_pk_mul_f32 v[92:93], v[92:93], v[0:1] op_sel_hi:[1,0]
	v_pk_mul_f32 v[90:91], v[90:91], v[0:1] op_sel_hi:[1,0]
	v_pk_mul_f32 v[88:89], v[88:89], v[0:1] op_sel_hi:[1,0]
	v_pk_mul_f32 v[86:87], v[86:87], v[0:1] op_sel_hi:[1,0]
	v_pk_mul_f32 v[84:85], v[84:85], v[0:1] op_sel_hi:[1,0]
	v_pk_mul_f32 v[82:83], v[82:83], v[0:1] op_sel_hi:[1,0]
	v_pk_mul_f32 v[80:81], v[80:81], v[0:1] op_sel_hi:[1,0]
	v_pk_mul_f32 v[78:79], v[78:79], v[0:1] op_sel_hi:[1,0]
	v_pk_mul_f32 v[76:77], v[76:77], v[0:1] op_sel_hi:[1,0]
	v_pk_mul_f32 v[74:75], v[74:75], v[0:1] op_sel_hi:[1,0]
	v_pk_mul_f32 v[72:73], v[72:73], v[0:1] op_sel_hi:[1,0]
	v_pk_mul_f32 v[70:71], v[70:71], v[0:1] op_sel_hi:[1,0]
	v_pk_mul_f32 v[68:69], v[68:69], v[0:1] op_sel_hi:[1,0]
	v_pk_mul_f32 v[66:67], v[66:67], v[0:1] op_sel_hi:[1,0]
; __device__ __forceinline__ void attn_unit(LAS unsigned char* lds, bf16_t* Zg, const unsigned char* KVg, int S, int b, int h, int qb, const float* lq1, const float* lk1, const float* lq2, const float* lk2, const float* subln_g, const float* rel_bias, bool dostore = true) {
;     ...
;     __builtin_amdgcn_s_setprio(0);
;     asm volatile("s_waitcnt vmcnt(0)" ::: "memory");
;     __syncthreads();
;     ...
;     { auto rr_ = __builtin_amdgcn_permlane32_swap(__float_as_uint(lsum), __float_as_uint(lsum), false, false); lsum = __uint_as_float(rr_[0]) + __uint_as_float(rr_[1]); }
;     const float lam = __builtin_amdgcn_exp2f(LOG2E * wave_sum(lq1[lane] * lk1[lane], lane)) - __builtin_amdgcn_exp2f(LOG2E * wave_sum(lq2[lane] * lk2[lane], lane)) + LAMBDA_INIT;
;     if (hi == 0) wsf[r32] = (mp == 1 ? lam : 1.0f) / lsum;
.LBB0_283:
	v_add_f32_e32 v0, v82, v83
	v_add_f32_e32 v99, v84, v85
	v_add_f32_e32 v0, v0, v99
	v_add_f32_e32 v0, 0, v0
	v_cvt_pk_bf16_f32 v175, v84, v85
	v_cvt_pk_bf16_f32 v174, v82, v83
	v_add_f32_e32 v82, v86, v87
	v_add_f32_e32 v83, v88, v89
	v_add_f32_e32 v82, v82, v83
	v_add_f32_e32 v0, v0, v82
	v_cvt_pk_bf16_f32 v177, v88, v89
	v_cvt_pk_bf16_f32 v176, v86, v87
	v_add_f32_e32 v82, v90, v91
	v_add_f32_e32 v83, v92, v93
	v_add_f32_e32 v82, v82, v83
	v_add_f32_e32 v0, v82, v0
	v_cvt_pk_bf16_f32 v170, v90, v91
	v_cvt_pk_bf16_f32 v171, v92, v93
	v_add_f32_e32 v82, v94, v95
	v_add_f32_e32 v83, v96, v97
	v_add_f32_e32 v82, v82, v83
	v_add_f32_e32 v0, v82, v0
	v_cvt_pk_bf16_f32 v172, v94, v95
	v_cvt_pk_bf16_f32 v173, v96, v97
	v_add_f32_e32 v82, v66, v67
	v_add_f32_e32 v83, v68, v69
	v_add_f32_e32 v82, v82, v83
	v_add_f32_e32 v0, v82, v0
	v_cvt_pk_bf16_f32 v166, v66, v67
	v_cvt_pk_bf16_f32 v167, v68, v69
	v_add_f32_e32 v66, v70, v71
	v_add_f32_e32 v67, v72, v73
	v_add_f32_e32 v66, v66, v67
	v_add_f32_e32 v0, v66, v0
	v_cvt_pk_bf16_f32 v168, v70, v71
	v_cvt_pk_bf16_f32 v169, v72, v73
	v_add_f32_e32 v66, v74, v75
	v_add_f32_e32 v67, v76, v77
	v_add_f32_e32 v66, v66, v67
	v_add_f32_e32 v0, v66, v0
	v_cvt_pk_bf16_f32 v162, v74, v75
	v_cvt_pk_bf16_f32 v163, v76, v77
	v_add_f32_e32 v66, v78, v79
	v_add_f32_e32 v67, v80, v81
	v_add_f32_e32 v66, v66, v67
	v_add_f32_e32 v0, v66, v0
	v_cvt_pk_bf16_f32 v164, v78, v79
	v_cvt_pk_bf16_f32 v165, v80, v81
	ds_read_b64_tr_b16 v[66:67], v214 offset:0
	ds_read_b64_tr_b16 v[68:69], v214 offset:512
	ds_read_b64_tr_b16 v[70:71], v214 offset:4096
	ds_read_b64_tr_b16 v[72:73], v214 offset:4608
	ds_read_b64_tr_b16 v[74:75], v214 offset:8192
	ds_read_b64_tr_b16 v[76:77], v214 offset:8704
	ds_read_b64_tr_b16 v[78:79], v214 offset:12288
	ds_read_b64_tr_b16 v[80:81], v214 offset:12800
	s_waitcnt lgkmcnt(6)
	s_nop 0
	s_nop 0
	v_mfma_f32_32x32x16_bf16 v[50:65], v[174:177], v[66:69], v[50:65]
	ds_read_b64_tr_b16 v[66:67], v214 offset:1024
	ds_read_b64_tr_b16 v[68:69], v214 offset:1536
	s_waitcnt lgkmcnt(6)
	v_mfma_f32_32x32x16_bf16 v[34:49], v[174:177], v[70:73], v[34:49]
	ds_read_b64_tr_b16 v[70:71], v214 offset:5120
	ds_read_b64_tr_b16 v[72:73], v214 offset:5632
	s_waitcnt lgkmcnt(6)
	v_mfma_f32_32x32x16_bf16 v[18:33], v[174:177], v[74:77], v[18:33]
	ds_read_b64_tr_b16 v[74:75], v214 offset:9216
	ds_read_b64_tr_b16 v[76:77], v214 offset:9728
	s_waitcnt lgkmcnt(6)
	v_mfma_f32_32x32x16_bf16 v[2:17], v[174:177], v[78:81], v[2:17]
	ds_read_b64_tr_b16 v[78:79], v214 offset:13312
	ds_read_b64_tr_b16 v[80:81], v214 offset:13824
	s_waitcnt lgkmcnt(6)
	v_mfma_f32_32x32x16_bf16 v[50:65], v[170:173], v[66:69], v[50:65]
	ds_read_b64_tr_b16 v[66:67], v214 offset:2048
	ds_read_b64_tr_b16 v[68:69], v214 offset:2560
	s_waitcnt lgkmcnt(6)
	v_mfma_f32_32x32x16_bf16 v[34:49], v[170:173], v[70:73], v[34:49]
	ds_read_b64_tr_b16 v[70:71], v214 offset:6144
	ds_read_b64_tr_b16 v[72:73], v214 offset:6656
	s_waitcnt lgkmcnt(6)
	v_mfma_f32_32x32x16_bf16 v[18:33], v[170:173], v[74:77], v[18:33]
	ds_read_b64_tr_b16 v[74:75], v214 offset:10240
	ds_read_b64_tr_b16 v[76:77], v214 offset:10752
	s_waitcnt lgkmcnt(6)
	v_mfma_f32_32x32x16_bf16 v[2:17], v[170:173], v[78:81], v[2:17]
	ds_read_b64_tr_b16 v[78:79], v214 offset:14336
	ds_read_b64_tr_b16 v[80:81], v214 offset:14848
	s_waitcnt lgkmcnt(6)
	v_mfma_f32_32x32x16_bf16 v[50:65], v[166:169], v[66:69], v[50:65]
	ds_read_b64_tr_b16 v[66:67], v214 offset:3072
	ds_read_b64_tr_b16 v[68:69], v214 offset:3584
	s_waitcnt lgkmcnt(6)
	v_mfma_f32_32x32x16_bf16 v[34:49], v[166:169], v[70:73], v[34:49]
	ds_read_b64_tr_b16 v[70:71], v214 offset:7168
	ds_read_b64_tr_b16 v[72:73], v214 offset:7680
	s_waitcnt lgkmcnt(6)
	v_mfma_f32_32x32x16_bf16 v[18:33], v[166:169], v[74:77], v[18:33]
	ds_read_b64_tr_b16 v[74:75], v214 offset:11264
	ds_read_b64_tr_b16 v[76:77], v214 offset:11776
	s_waitcnt lgkmcnt(6)
	v_mfma_f32_32x32x16_bf16 v[2:17], v[166:169], v[78:81], v[2:17]
	ds_read_b64_tr_b16 v[78:79], v214 offset:15360
	ds_read_b64_tr_b16 v[80:81], v214 offset:15872
	s_waitcnt lgkmcnt(6)
	v_mfma_f32_32x32x16_bf16 v[50:65], v[162:165], v[66:69], v[50:65]
	s_waitcnt lgkmcnt(4)
	v_mfma_f32_32x32x16_bf16 v[34:49], v[162:165], v[70:73], v[34:49]
	s_waitcnt lgkmcnt(2)
	v_mfma_f32_32x32x16_bf16 v[18:33], v[162:165], v[74:77], v[18:33]
	s_waitcnt lgkmcnt(0)
	v_mfma_f32_32x32x16_bf16 v[2:17], v[162:165], v[78:81], v[2:17]
	v_add_f32_e32 v0, v98, v0
	s_setprio 0
	v_lshlrev_b32_e32 v66, 2, v209
	s_waitcnt vmcnt(0)
	s_waitcnt vmcnt(0)
	s_barrier
	global_load_dword v67, v66, s[74:75]
	global_load_dword v68, v66, s[76:77]
	global_load_dword v69, v66, s[70:71]
	global_load_dword v70, v66, s[72:73]
	v_xor_b32_e32 v84, 4, v66
	v_xor_b32_e32 v85, 8, v66
	v_xor_b32_e32 v86, 16, v66
	v_xor_b32_e32 v87, 32, v66
	v_xor_b32_e32 v88, 64, v66
	v_xor_b32_e32 v66, 0x80, v66
	s_waitcnt vmcnt(2)
	v_mul_f32_e32 v71, v67, v68
	ds_bpermute_b32 v71, v84, v71
	s_waitcnt vmcnt(0)
	v_mul_f32_e32 v72, v69, v70
	ds_bpermute_b32 v72, v84, v72
	s_waitcnt lgkmcnt(1)
	v_fmac_f32_e32 v71, v67, v68
	ds_bpermute_b32 v67, v85, v71
	s_waitcnt lgkmcnt(1)
	v_fmac_f32_e32 v72, v69, v70
	ds_bpermute_b32 v68, v85, v72
	s_waitcnt lgkmcnt(1)
	v_add_f32_e32 v67, v71, v67
	ds_bpermute_b32 v69, v86, v67
	s_waitcnt lgkmcnt(1)
	v_add_f32_e32 v68, v72, v68
	ds_bpermute_b32 v70, v86, v68
	s_waitcnt lgkmcnt(1)
	v_add_f32_e32 v67, v67, v69
	ds_bpermute_b32 v69, v87, v67
	s_waitcnt lgkmcnt(1)
	v_add_f32_e32 v68, v68, v70
	ds_bpermute_b32 v70, v87, v68
	s_waitcnt lgkmcnt(1)
	v_add_f32_e32 v67, v67, v69
	ds_bpermute_b32 v69, v88, v67
	s_waitcnt lgkmcnt(1)
	v_add_f32_e32 v68, v68, v70
	ds_bpermute_b32 v70, v88, v68
	s_waitcnt lgkmcnt(1)
	v_add_f32_e32 v67, v67, v69
	s_waitcnt lgkmcnt(0)
	v_add_f32_e32 v69, v68, v70
	ds_bpermute_b32 v68, v66, v67
	ds_bpermute_b32 v70, v66, v69
	v_mov_b32_e32 v66, v0
	s_nop 1
	v_permlane32_swap_b32_e32 v0, v66
	s_and_saveexec_b64 s[6:7], s[4:5]
	s_cbranch_execz .LBB0_285
	s_waitcnt lgkmcnt(0)
	v_add_f32_e32 v69, v69, v70
	v_add_f32_e32 v67, v67, v68
	v_mul_f32_e32 v67, 0x3fb8aa3b, v67
	v_mul_f32_e32 v68, 0x3fb8aa3b, v69
	v_exp_f32_e32 v67, v67
	v_exp_f32_e32 v68, v68
	s_cmp_eq_u32 s89, 1
	s_cselect_b64 vcc, -1, 0
	v_add_f32_e32 v0, v0, v66
	v_sub_f32_e32 v67, v67, v68
	v_add_f32_e32 v67, 0x3e4ccccd, v67
	v_cndmask_b32_e32 v66, 1.0, v67, vcc
	v_div_scale_f32 v67, s[4:5], v0, v0, v66
	v_rcp_f32_e32 v68, v67
	s_nop 0
	v_fma_f32 v69, -v67, v68, 1.0
	v_fmac_f32_e32 v68, v69, v68
	v_div_scale_f32 v69, vcc, v66, v0, v66
	v_mul_f32_e32 v70, v69, v68
	v_fma_f32 v71, -v67, v70, v69
	v_fmac_f32_e32 v70, v71, v68
	v_fma_f32 v67, -v67, v70, v69
	v_div_fmas_f32 v67, v67, v68, v70
	v_div_fixup_f32 v0, v67, v0, v66
	ds_write_b32 v213, v0
